# v23 + top-k search early-out when fewer than 16 candidate blocks (T=0, exact)
# speedup vs baseline: 1.0050x; 1.0021x over previous
.LBB0_833:
	s_or_b64 exec, exec, s[12:13]
	s_mov_b32 s12, 0
	v_cmp_ne_u32_e64 s[10:11], 0, v3
	s_bcnt1_i32_b64 s30, s[10:11]
	s_cmp_lt_u32 s30, 16
	s_cbranch_scc1 .Ltopk_done
	s_or_b32 s13, s12, 0x10000000
	v_cmp_le_u32_e64 s[10:11], s13, v3
	s_bcnt1_i32_b64 s30, s[10:11]
	s_cmp_gt_u32 s30, 15
	s_cselect_b32 s12, s13, s12
	s_or_b32 s13, s12, 0x8000000
	v_cmp_le_u32_e64 s[10:11], s13, v3
	s_bcnt1_i32_b64 s30, s[10:11]
	s_cmp_gt_u32 s30, 15
	s_cselect_b32 s12, s13, s12
	s_or_b32 s13, s12, 0x4000000
	v_cmp_le_u32_e64 s[10:11], s13, v3
	s_bcnt1_i32_b64 s30, s[10:11]
	s_cmp_gt_u32 s30, 15
	s_cselect_b32 s12, s13, s12
	s_or_b32 s13, s12, 0x2000000
	v_cmp_le_u32_e64 s[10:11], s13, v3
	s_bcnt1_i32_b64 s30, s[10:11]
	s_cmp_gt_u32 s30, 15
	s_cselect_b32 s12, s13, s12
	s_or_b32 s13, s12, 0x1000000
	v_cmp_le_u32_e64 s[10:11], s13, v3
	s_bcnt1_i32_b64 s30, s[10:11]
	s_cmp_gt_u32 s30, 15
	s_cselect_b32 s12, s13, s12
	s_or_b32 s13, s12, 0x800000
	v_cmp_le_u32_e64 s[10:11], s13, v3
	s_bcnt1_i32_b64 s30, s[10:11]
	s_cmp_gt_u32 s30, 15
	s_cselect_b32 s12, s13, s12
	s_or_b32 s13, s12, 0x400000
	v_cmp_le_u32_e64 s[10:11], s13, v3
	s_bcnt1_i32_b64 s30, s[10:11]
	s_cmp_gt_u32 s30, 15
	s_cselect_b32 s12, s13, s12
	s_or_b32 s13, s12, 0x200000
	v_cmp_le_u32_e64 s[10:11], s13, v3
	s_bcnt1_i32_b64 s30, s[10:11]
	s_cmp_gt_u32 s30, 15
	s_cselect_b32 s12, s13, s12
	s_or_b32 s13, s12, 0x100000
	v_cmp_le_u32_e64 s[10:11], s13, v3
	s_bcnt1_i32_b64 s30, s[10:11]
	s_cmp_gt_u32 s30, 15
	s_cselect_b32 s12, s13, s12
	s_or_b32 s13, s12, 0x80000
	v_cmp_le_u32_e64 s[10:11], s13, v3
	s_bcnt1_i32_b64 s30, s[10:11]
	s_cmp_gt_u32 s30, 15
	s_cselect_b32 s12, s13, s12
	s_or_b32 s13, s12, 0x40000
	v_cmp_le_u32_e64 s[10:11], s13, v3
	s_bcnt1_i32_b64 s30, s[10:11]
	s_cmp_gt_u32 s30, 15
	s_cselect_b32 s12, s13, s12
	s_or_b32 s13, s12, 0x20000
	v_cmp_le_u32_e64 s[10:11], s13, v3
	s_bcnt1_i32_b64 s30, s[10:11]
	s_cmp_gt_u32 s30, 15
	s_cselect_b32 s12, s13, s12
	s_or_b32 s13, s12, 0x10000
	v_cmp_le_u32_e64 s[10:11], s13, v3
	s_bcnt1_i32_b64 s30, s[10:11]
	s_cmp_gt_u32 s30, 15
	s_cselect_b32 s12, s13, s12
	s_or_b32 s13, s12, 0x8000
	v_cmp_le_u32_e64 s[10:11], s13, v3
	s_bcnt1_i32_b64 s30, s[10:11]
	s_cmp_gt_u32 s30, 15
	s_cselect_b32 s12, s13, s12
	s_or_b32 s13, s12, 0x4000
	v_cmp_le_u32_e64 s[10:11], s13, v3
	s_bcnt1_i32_b64 s30, s[10:11]
	s_cmp_gt_u32 s30, 15
	s_cselect_b32 s12, s13, s12
	s_or_b32 s13, s12, 0x2000
	v_cmp_le_u32_e64 s[10:11], s13, v3
	s_bcnt1_i32_b64 s30, s[10:11]
	s_cmp_gt_u32 s30, 15
	s_cselect_b32 s12, s13, s12
	s_or_b32 s13, s12, 0x1000
	v_cmp_le_u32_e64 s[10:11], s13, v3
	s_bcnt1_i32_b64 s30, s[10:11]
	s_cmp_gt_u32 s30, 15
	s_cselect_b32 s12, s13, s12
	s_or_b32 s13, s12, 0x800
	v_cmp_le_u32_e64 s[10:11], s13, v3
	s_bcnt1_i32_b64 s30, s[10:11]
	s_cmp_gt_u32 s30, 15
	s_cselect_b32 s12, s13, s12
	s_or_b32 s13, s12, 0x400
	v_cmp_le_u32_e64 s[10:11], s13, v3
	s_bcnt1_i32_b64 s30, s[10:11]
	s_cmp_gt_u32 s30, 15
	s_cselect_b32 s12, s13, s12
	s_or_b32 s13, s12, 0x200
	v_cmp_le_u32_e64 s[10:11], s13, v3
	s_bcnt1_i32_b64 s30, s[10:11]
	s_cmp_gt_u32 s30, 15
	s_cselect_b32 s12, s13, s12
	s_or_b32 s13, s12, 0x100
	v_cmp_le_u32_e64 s[10:11], s13, v3
	s_bcnt1_i32_b64 s30, s[10:11]
	s_cmp_gt_u32 s30, 15
	s_cselect_b32 s12, s13, s12
	s_or_b32 s13, s12, 0x80
	v_cmp_le_u32_e64 s[10:11], s13, v3
	s_bcnt1_i32_b64 s30, s[10:11]
	s_cmp_gt_u32 s30, 15
	s_cselect_b32 s12, s13, s12
	s_or_b32 s13, s12, 64
	v_cmp_le_u32_e64 s[10:11], s13, v3
	s_bcnt1_i32_b64 s30, s[10:11]
	s_cmp_gt_u32 s30, 15
	s_cselect_b32 s12, s13, s12
	s_or_b32 s13, s12, 32
	v_cmp_le_u32_e64 s[10:11], s13, v3
	s_bcnt1_i32_b64 s30, s[10:11]
	s_cmp_gt_u32 s30, 15
	s_cselect_b32 s12, s13, s12
	s_or_b32 s13, s12, 16
	v_cmp_le_u32_e64 s[10:11], s13, v3
	s_bcnt1_i32_b64 s30, s[10:11]
	s_cmp_gt_u32 s30, 15
	s_cselect_b32 s12, s13, s12
	s_or_b32 s13, s12, 8
	v_cmp_le_u32_e64 s[10:11], s13, v3
	s_bcnt1_i32_b64 s30, s[10:11]
	s_cmp_gt_u32 s30, 15
	s_cselect_b32 s12, s13, s12
	s_or_b32 s13, s12, 4
	v_cmp_le_u32_e64 s[10:11], s13, v3
	s_bcnt1_i32_b64 s30, s[10:11]
	s_cmp_gt_u32 s30, 15
	s_cselect_b32 s12, s13, s12
	s_or_b32 s13, s12, 2
	v_cmp_le_u32_e64 s[10:11], s13, v3
	s_bcnt1_i32_b64 s30, s[10:11]
	s_cmp_gt_u32 s30, 15
	s_cselect_b32 s12, s13, s12
	s_or_b32 s13, s12, 1
	v_cmp_le_u32_e64 s[10:11], s13, v3
	s_bcnt1_i32_b64 s30, s[10:11]
	s_cmp_gt_u32 s30, 15
	s_cselect_b32 s12, s13, s12
.Ltopk_done:
	v_cmp_lt_u32_e64 s[10:11], s12, v3
	s_cmp_lg_u32 s12, 0
	s_cselect_b64 s[16:17], -1, 0
	s_bcnt1_i32_b64 s13, s[10:11]
	s_sub_i32 s18, 16, s13
	v_cmp_eq_u32_e64 s[12:13], s12, v3
	s_and_b64 s[16:17], s[16:17], s[12:13]
	v_cndmask_b32_e64 v3, 0, 1, s[16:17]
	v_cmp_ne_u32_e64 s[12:13], 0, v3
	s_nop 1
	v_mbcnt_lo_u32_b32 v3, s12, 0
	v_mbcnt_hi_u32_b32 v3, s13, v3
	v_cmp_gt_i32_e64 s[12:13], s18, v3
	s_and_b64 s[12:13], s[16:17], s[12:13]
	s_or_b64 s[10:11], s[10:11], s[12:13]
	v_cndmask_b32_e64 v3, 0, 1, s[10:11]
	v_cmp_ne_u32_e64 s[16:17], 0, v3
	s_and_saveexec_b64 s[12:13], vcc
	s_cbranch_execz .LBB0_830
	v_mov_b32_e32 v3, s21
	v_mov_b64_e32 v[4:5], s[16:17]
	s_cmp_eq_u64 s[16:17], 0
	ds_write_b64 v3, v[4:5]
	s_cbranch_scc1 .LBB0_829
	v_mbcnt_lo_u32_b32 v3, exec_lo, 0
	v_mbcnt_hi_u32_b32 v3, exec_hi, v3
	v_cmp_eq_u32_e64 s[10:11], 0, v3
	s_and_saveexec_b64 s[18:19], s[10:11]
	s_cbranch_execz .LBB0_828
	v_mov_b32_e32 v3, s85
	v_mov_b64_e32 v[4:5], s[16:17]
	ds_or_b64 v3, v[4:5]
	s_branch .LBB0_828
